# last layer's down-projection epilogue: residual-stream stores also paired into full 128-B lines (first result kept in spare registers until the second is ready)
# speedup vs baseline: 1.0051x; 1.0051x over previous
;     __device__ __forceinline__ void operator()(const f32x4 (&acc)[2][2][4][2], const pg8::Unit& u, int wr, int wc, int fr, int fq) const {
;     ...
;                 const int R = rowbase + u.pm * 256 + ai * 128 + wr * 64 + m * 16 + fr;
;                 const bool islat = R < TL; const int mrow = islat ? (R >> 13) : 8;
;                 const float* src = islat ? rin_l + (size_t)R * DM : rin_c + (size_t)(R - TL) * DM;
;                 float* dst = islat ? rout_l + (size_t)R * DM : rout_c + (size_t)(R - TL) * DM;
;                 const float* gp = gate + (size_t)mrow * MODW;
; #pragma unroll
;                 for (int bj = 0; bj < 2; ++bj)
; #pragma unroll
;                     for (int n = 0; n < 2; ++n) { const int c = u.pn * 256 + bj * 128 + wc * 32 + 8 * fq + 4 * n;
;                         const f32x4 g4 = *(const f32x4*)(gp + c), x4 = *(const f32x4*)(src + c);
;                         *(f32x4*)(dst + c) = x4 + g4 * acc[ai][bj][m][n]; } }
.LBB0_1298:
	v_lshl_add_u32 v150, s34, 8, v142
	s_mov_b32 s100, 0xaaaaaaaa
	s_mov_b32 s101, 0xaaaaaaaa
	v_mov_b32_e32 v222, 0x1000
	v_mov_b32_e32 v223, 16
	v_cndmask_b32_e64 v242, v222, v223, s[100:101]
	v_mov_b32_e32 v243, 0
	v_add_u32_e32 v151, s52, v150
	v_add_u32_e32 v146, 0xffff0000, v151
	v_ashrrev_i32_e32 v147, 31, v151
	v_cmp_gt_i32_e32 vcc, s33, v151
	v_min_i32_e32 v141, 0x10000, v151
	v_mov_b32_e32 v148, s55
	v_cndmask_b32_e32 v153, 0, v147, vcc
	v_cndmask_b32_e32 v152, v146, v151, vcc
	v_mov_b32_e32 v146, s56
	v_mov_b32_e32 v147, s45
	v_mov_b32_e32 v149, s44
	v_ashrrev_i32_e32 v141, 13, v141
	v_cndmask_b32_e32 v155, v146, v147, vcc
	v_cndmask_b32_e32 v154, v148, v149, vcc
	v_lshlrev_b64 v[152:153], 12, v[152:153]
	v_lshl_or_b32 v140, s35, 8, v144
	v_lshl_add_u64 v[156:157], v[154:155], 0, v[152:153]
	v_mul_i32_i24_e32 v152, 0x1800, v141
	v_ashrrev_i32_e32 v153, 31, v152
	v_ashrrev_i32_e32 v141, 31, v140
	v_lshl_add_u64 v[152:153], v[152:153], 2, s[20:21]
	v_lshlrev_b64 v[140:141], 2, v[140:141]
	v_lshl_add_u64 v[160:161], v[152:153], 0, v[140:141]
	global_load_dwordx4 v[152:155], v[160:161], off
	v_lshl_add_u64 v[180:181], v[156:157], 0, v[140:141]
	v_lshl_add_u64 v[226:227], v[180:181], 0, v[242:243]
	global_load_dwordx4 v[214:217], v[226:227], off offset:-4096
	global_load_dwordx4 v[218:221], v[226:227], off
	s_mov_b64 s[34:35], -1
	s_waitcnt vmcnt(0)
	v_cndmask_b32_e64 v222, v218, v214, s[100:101]
	v_cndmask_b32_e64 v223, v219, v215, s[100:101]
	v_cndmask_b32_e64 v224, v220, v216, s[100:101]
	v_cndmask_b32_e64 v225, v221, v217, s[100:101]
	v_mov_b32_dpp v238, v222 quad_perm:[1,0,3,2] row_mask:0xf bank_mask:0xf
	v_mov_b32_dpp v239, v223 quad_perm:[1,0,3,2] row_mask:0xf bank_mask:0xf
	v_mov_b32_dpp v240, v224 quad_perm:[1,0,3,2] row_mask:0xf bank_mask:0xf
	v_mov_b32_dpp v241, v225 quad_perm:[1,0,3,2] row_mask:0xf bank_mask:0xf
	v_cndmask_b32_e64 v156, v214, v238, s[100:101]
	v_cndmask_b32_e64 v176, v238, v218, s[100:101]
	v_cndmask_b32_e64 v157, v215, v239, s[100:101]
	v_cndmask_b32_e64 v177, v239, v219, s[100:101]
	v_cndmask_b32_e64 v158, v216, v240, s[100:101]
	v_cndmask_b32_e64 v178, v240, v220, s[100:101]
	v_cndmask_b32_e64 v159, v217, v241, s[100:101]
	v_cndmask_b32_e64 v179, v241, v221, s[100:101]
	v_pk_fma_f32 v[128:129], v[128:129], v[154:155], v[158:159]
	v_pk_fma_f32 v[126:127], v[126:127], v[152:153], v[156:157]
	v_mov_b32_e32 v244, v126
	v_mov_b32_e32 v245, v127
	v_mov_b32_e32 v246, v128
	v_mov_b32_e32 v247, v129
	global_load_dwordx4 v[126:129], v[160:161], off offset:16
	s_waitcnt vmcnt(0)
	v_pk_fma_f32 v[124:125], v[124:125], v[128:129], v[178:179]
	v_pk_fma_f32 v[122:123], v[122:123], v[126:127], v[176:177]
	v_cndmask_b32_e64 v222, v122, v244, s[100:101]
	v_cndmask_b32_e64 v223, v123, v245, s[100:101]
	v_cndmask_b32_e64 v224, v124, v246, s[100:101]
	v_cndmask_b32_e64 v225, v125, v247, s[100:101]
	v_mov_b32_dpp v238, v222 quad_perm:[1,0,3,2] row_mask:0xf bank_mask:0xf
	v_mov_b32_dpp v239, v223 quad_perm:[1,0,3,2] row_mask:0xf bank_mask:0xf
	v_mov_b32_dpp v240, v224 quad_perm:[1,0,3,2] row_mask:0xf bank_mask:0xf
	v_mov_b32_dpp v241, v225 quad_perm:[1,0,3,2] row_mask:0xf bank_mask:0xf
	v_cndmask_b32_e64 v214, v244, v238, s[100:101]
	v_cndmask_b32_e64 v218, v238, v122, s[100:101]
	v_cndmask_b32_e64 v215, v245, v239, s[100:101]
	v_cndmask_b32_e64 v219, v239, v123, s[100:101]
	v_cndmask_b32_e64 v216, v246, v240, s[100:101]
	v_cndmask_b32_e64 v220, v240, v124, s[100:101]
	v_cndmask_b32_e64 v217, v247, v241, s[100:101]
	v_cndmask_b32_e64 v221, v241, v125, s[100:101]
	v_lshl_add_u64 v[226:227], v[180:181], 0, v[242:243]
	global_store_dwordx4 v[226:227], v[214:217], off offset:-4096
	global_store_dwordx4 v[226:227], v[218:221], off
	global_load_dwordx4 v[122:125], v[160:161], off offset:512
	s_nop 0
	v_lshl_add_u64 v[226:227], v[180:181], 0, v[242:243]
	global_load_dwordx4 v[214:217], v[226:227], off offset:-3584
	global_load_dwordx4 v[218:221], v[226:227], off offset:512
	s_waitcnt vmcnt(0)
	v_cndmask_b32_e64 v222, v218, v214, s[100:101]
	v_cndmask_b32_e64 v223, v219, v215, s[100:101]
	v_cndmask_b32_e64 v224, v220, v216, s[100:101]
	v_cndmask_b32_e64 v225, v221, v217, s[100:101]
	v_mov_b32_dpp v238, v222 quad_perm:[1,0,3,2] row_mask:0xf bank_mask:0xf
	v_mov_b32_dpp v239, v223 quad_perm:[1,0,3,2] row_mask:0xf bank_mask:0xf
	v_mov_b32_dpp v240, v224 quad_perm:[1,0,3,2] row_mask:0xf bank_mask:0xf
	v_mov_b32_dpp v241, v225 quad_perm:[1,0,3,2] row_mask:0xf bank_mask:0xf
	v_cndmask_b32_e64 v126, v214, v238, s[100:101]
	v_cndmask_b32_e64 v152, v238, v218, s[100:101]
	v_cndmask_b32_e64 v127, v215, v239, s[100:101]
	v_cndmask_b32_e64 v153, v239, v219, s[100:101]
	v_cndmask_b32_e64 v128, v216, v240, s[100:101]
	v_cndmask_b32_e64 v154, v240, v220, s[100:101]
	v_cndmask_b32_e64 v129, v217, v241, s[100:101]
	v_cndmask_b32_e64 v155, v241, v221, s[100:101]
	v_pk_fma_f32 v[120:121], v[120:121], v[124:125], v[128:129]
	v_pk_fma_f32 v[118:119], v[118:119], v[122:123], v[126:127]
	v_mov_b32_e32 v244, v118
	v_mov_b32_e32 v245, v119
	v_mov_b32_e32 v246, v120
	v_mov_b32_e32 v247, v121
	global_load_dwordx4 v[118:121], v[160:161], off offset:528
	v_add_u32_e32 v122, 16, v151
	v_min_i32_e32 v123, 0x10000, v122
	v_add_u32_e32 v124, 0xffff0010, v151
	v_ashrrev_i32_e32 v125, 31, v122
	v_ashrrev_i32_e32 v126, 13, v123
	v_cmp_gt_i32_e32 vcc, s33, v122
	v_mul_i32_i24_e32 v126, 0x1800, v126
	v_ashrrev_i32_e32 v127, 31, v126
	v_cndmask_b32_e32 v123, 0, v125, vcc
	v_cndmask_b32_e32 v122, v124, v122, vcc
	v_cndmask_b32_e32 v125, v146, v147, vcc
	v_cndmask_b32_e32 v124, v148, v149, vcc
	v_lshlrev_b64 v[122:123], 12, v[122:123]
	v_lshl_add_u64 v[122:123], v[124:125], 0, v[122:123]
	v_lshl_add_u64 v[124:125], v[126:127], 2, s[20:21]
	v_lshl_add_u64 v[128:129], v[124:125], 0, v[140:141]
	v_lshl_add_u64 v[126:127], v[122:123], 0, v[140:141]
	s_waitcnt vmcnt(0)
;     __device__ __forceinline__ void operator()(const f32x4 (&acc)[2][2][4][2], const pg8::Unit& u, int wr, int wc, int fr, int fq) const {
;     ...
;                 const int R = rowbase + u.pm * 256 + ai * 128 + wr * 64 + m * 16 + fr;
;                 const bool islat = R < TL; const int mrow = islat ? (R >> 13) : 8;
;                 const float* src = islat ? rin_l + (size_t)R * DM : rin_c + (size_t)(R - TL) * DM;
;                 float* dst = islat ? rout_l + (size_t)R * DM : rout_c + (size_t)(R - TL) * DM;
;                 const float* gp = gate + (size_t)mrow * MODW;
; #pragma unroll
;                 for (int bj = 0; bj < 2; ++bj)
; #pragma unroll
;                     for (int n = 0; n < 2; ++n) { const int c = u.pn * 256 + bj * 128 + wc * 32 + 8 * fq + 4 * n;
;                         const f32x4 g4 = *(const f32x4*)(gp + c), x4 = *(const f32x4*)(src + c);
;                         *(f32x4*)(dst + c) = x4 + g4 * acc[ai][bj][m][n]; } }
	v_pk_fma_f32 v[108:109], v[108:109], v[120:121], v[154:155]
	v_pk_fma_f32 v[106:107], v[106:107], v[118:119], v[152:153]
	v_cndmask_b32_e64 v222, v106, v244, s[100:101]
	v_cndmask_b32_e64 v223, v107, v245, s[100:101]
	v_cndmask_b32_e64 v224, v108, v246, s[100:101]
	v_cndmask_b32_e64 v225, v109, v247, s[100:101]
	v_mov_b32_dpp v238, v222 quad_perm:[1,0,3,2] row_mask:0xf bank_mask:0xf
	v_mov_b32_dpp v239, v223 quad_perm:[1,0,3,2] row_mask:0xf bank_mask:0xf
	v_mov_b32_dpp v240, v224 quad_perm:[1,0,3,2] row_mask:0xf bank_mask:0xf
	v_mov_b32_dpp v241, v225 quad_perm:[1,0,3,2] row_mask:0xf bank_mask:0xf
	v_cndmask_b32_e64 v214, v244, v238, s[100:101]
	v_cndmask_b32_e64 v218, v238, v106, s[100:101]
	v_cndmask_b32_e64 v215, v245, v239, s[100:101]
	v_cndmask_b32_e64 v219, v239, v107, s[100:101]
	v_cndmask_b32_e64 v216, v246, v240, s[100:101]
	v_cndmask_b32_e64 v220, v240, v108, s[100:101]
	v_cndmask_b32_e64 v217, v247, v241, s[100:101]
	v_cndmask_b32_e64 v221, v241, v109, s[100:101]
	v_lshl_add_u64 v[226:227], v[180:181], 0, v[242:243]
	global_store_dwordx4 v[226:227], v[214:217], off offset:-3584
	global_store_dwordx4 v[226:227], v[218:221], off offset:512
	global_load_dwordx4 v[106:109], v[128:129], off
	s_nop 0
	v_lshl_add_u64 v[226:227], v[126:127], 0, v[242:243]
	global_load_dwordx4 v[214:217], v[226:227], off offset:-4096
	global_load_dwordx4 v[218:221], v[226:227], off
	s_waitcnt vmcnt(0)
	v_cndmask_b32_e64 v222, v218, v214, s[100:101]
	v_cndmask_b32_e64 v223, v219, v215, s[100:101]
	v_cndmask_b32_e64 v224, v220, v216, s[100:101]
	v_cndmask_b32_e64 v225, v221, v217, s[100:101]
	v_mov_b32_dpp v238, v222 quad_perm:[1,0,3,2] row_mask:0xf bank_mask:0xf
	v_mov_b32_dpp v239, v223 quad_perm:[1,0,3,2] row_mask:0xf bank_mask:0xf
	v_mov_b32_dpp v240, v224 quad_perm:[1,0,3,2] row_mask:0xf bank_mask:0xf
	v_mov_b32_dpp v241, v225 quad_perm:[1,0,3,2] row_mask:0xf bank_mask:0xf
	v_cndmask_b32_e64 v118, v214, v238, s[100:101]
	v_cndmask_b32_e64 v122, v238, v218, s[100:101]
	v_cndmask_b32_e64 v119, v215, v239, s[100:101]
	v_cndmask_b32_e64 v123, v239, v219, s[100:101]
	v_cndmask_b32_e64 v120, v216, v240, s[100:101]
	v_cndmask_b32_e64 v124, v240, v220, s[100:101]
	v_cndmask_b32_e64 v121, v217, v241, s[100:101]
	v_cndmask_b32_e64 v125, v241, v221, s[100:101]
	v_pk_fma_f32 v[108:109], v[116:117], v[108:109], v[120:121]
	v_pk_fma_f32 v[106:107], v[114:115], v[106:107], v[118:119]
	v_mov_b32_e32 v244, v106
	v_mov_b32_e32 v245, v107
	v_mov_b32_e32 v246, v108
	v_mov_b32_e32 v247, v109
	global_load_dwordx4 v[106:109], v[128:129], off offset:16
	s_waitcnt vmcnt(0)
	v_pk_fma_f32 v[108:109], v[112:113], v[108:109], v[124:125]
	v_pk_fma_f32 v[106:107], v[110:111], v[106:107], v[122:123]
	v_cndmask_b32_e64 v222, v106, v244, s[100:101]
	v_cndmask_b32_e64 v223, v107, v245, s[100:101]
	v_cndmask_b32_e64 v224, v108, v246, s[100:101]
	v_cndmask_b32_e64 v225, v109, v247, s[100:101]
	v_mov_b32_dpp v238, v222 quad_perm:[1,0,3,2] row_mask:0xf bank_mask:0xf
	v_mov_b32_dpp v239, v223 quad_perm:[1,0,3,2] row_mask:0xf bank_mask:0xf
	v_mov_b32_dpp v240, v224 quad_perm:[1,0,3,2] row_mask:0xf bank_mask:0xf
	v_mov_b32_dpp v241, v225 quad_perm:[1,0,3,2] row_mask:0xf bank_mask:0xf
	v_cndmask_b32_e64 v214, v244, v238, s[100:101]
	v_cndmask_b32_e64 v218, v238, v106, s[100:101]
	v_cndmask_b32_e64 v215, v245, v239, s[100:101]
	v_cndmask_b32_e64 v219, v239, v107, s[100:101]
	v_cndmask_b32_e64 v216, v246, v240, s[100:101]
	v_cndmask_b32_e64 v220, v240, v108, s[100:101]
	v_cndmask_b32_e64 v217, v247, v241, s[100:101]
	v_cndmask_b32_e64 v221, v241, v109, s[100:101]
	v_lshl_add_u64 v[226:227], v[126:127], 0, v[242:243]
	global_store_dwordx4 v[226:227], v[214:217], off offset:-4096
	global_store_dwordx4 v[226:227], v[218:221], off
	global_load_dwordx4 v[106:109], v[128:129], off offset:512
	s_nop 0
	v_lshl_add_u64 v[226:227], v[126:127], 0, v[242:243]
	global_load_dwordx4 v[214:217], v[226:227], off offset:-3584
	global_load_dwordx4 v[218:221], v[226:227], off offset:512
	s_waitcnt vmcnt(0)
	v_cndmask_b32_e64 v222, v218, v214, s[100:101]
	v_cndmask_b32_e64 v223, v219, v215, s[100:101]
	v_cndmask_b32_e64 v224, v220, v216, s[100:101]
	v_cndmask_b32_e64 v225, v221, v217, s[100:101]
	v_mov_b32_dpp v238, v222 quad_perm:[1,0,3,2] row_mask:0xf bank_mask:0xf
	v_mov_b32_dpp v239, v223 quad_perm:[1,0,3,2] row_mask:0xf bank_mask:0xf
	v_mov_b32_dpp v240, v224 quad_perm:[1,0,3,2] row_mask:0xf bank_mask:0xf
	v_mov_b32_dpp v241, v225 quad_perm:[1,0,3,2] row_mask:0xf bank_mask:0xf
	v_cndmask_b32_e64 v110, v214, v238, s[100:101]
	v_cndmask_b32_e64 v114, v238, v218, s[100:101]
	v_cndmask_b32_e64 v111, v215, v239, s[100:101]
	v_cndmask_b32_e64 v115, v239, v219, s[100:101]
	v_cndmask_b32_e64 v112, v216, v240, s[100:101]
	v_cndmask_b32_e64 v116, v240, v220, s[100:101]
	v_cndmask_b32_e64 v113, v217, v241, s[100:101]
	v_cndmask_b32_e64 v117, v241, v221, s[100:101]
	v_pk_fma_f32 v[104:105], v[104:105], v[108:109], v[112:113]
	v_pk_fma_f32 v[102:103], v[102:103], v[106:107], v[110:111]
	v_mov_b32_e32 v244, v102
	v_mov_b32_e32 v245, v103
	v_mov_b32_e32 v246, v104
	v_mov_b32_e32 v247, v105
	global_load_dwordx4 v[102:105], v[128:129], off offset:528
	v_add_u32_e32 v106, 32, v151
	v_min_i32_e32 v107, 0x10000, v106
	v_add_u32_e32 v108, 0xffff0020, v151
	v_ashrrev_i32_e32 v109, 31, v106
	v_ashrrev_i32_e32 v110, 13, v107
	v_cmp_gt_i32_e32 vcc, s33, v106
	v_mul_i32_i24_e32 v110, 0x1800, v110
	v_ashrrev_i32_e32 v111, 31, v110
	v_cndmask_b32_e32 v107, 0, v109, vcc
	v_cndmask_b32_e32 v106, v108, v106, vcc
	v_cndmask_b32_e32 v109, v146, v147, vcc
	v_cndmask_b32_e32 v108, v148, v149, vcc
	v_lshlrev_b64 v[106:107], 12, v[106:107]
	v_lshl_add_u64 v[106:107], v[108:109], 0, v[106:107]
	v_lshl_add_u64 v[108:109], v[110:111], 2, s[20:21]
	v_lshl_add_u64 v[112:113], v[108:109], 0, v[140:141]
	v_lshl_add_u64 v[110:111], v[106:107], 0, v[140:141]
	s_waitcnt vmcnt(0)
;     __device__ __forceinline__ void operator()(const f32x4 (&acc)[2][2][4][2], const pg8::Unit& u, int wr, int wc, int fr, int fq) const {
;     ...
;                 const int R = rowbase + u.pm * 256 + ai * 128 + wr * 64 + m * 16 + fr;
;                 const bool islat = R < TL; const int mrow = islat ? (R >> 13) : 8;
;                 const float* src = islat ? rin_l + (size_t)R * DM : rin_c + (size_t)(R - TL) * DM;
;                 float* dst = islat ? rout_l + (size_t)R * DM : rout_c + (size_t)(R - TL) * DM;
;                 const float* gp = gate + (size_t)mrow * MODW;
; #pragma unroll
;                 for (int bj = 0; bj < 2; ++bj)
; #pragma unroll
;                     for (int n = 0; n < 2; ++n) { const int c = u.pn * 256 + bj * 128 + wc * 32 + 8 * fq + 4 * n;
;                         const f32x4 g4 = *(const f32x4*)(gp + c), x4 = *(const f32x4*)(src + c);
;                         *(f32x4*)(dst + c) = x4 + g4 * acc[ai][bj][m][n]; } }
	v_pk_fma_f32 v[92:93], v[92:93], v[104:105], v[116:117]
	v_pk_fma_f32 v[90:91], v[90:91], v[102:103], v[114:115]
	v_cndmask_b32_e64 v222, v90, v244, s[100:101]
	v_cndmask_b32_e64 v223, v91, v245, s[100:101]
	v_cndmask_b32_e64 v224, v92, v246, s[100:101]
	v_cndmask_b32_e64 v225, v93, v247, s[100:101]
	v_mov_b32_dpp v238, v222 quad_perm:[1,0,3,2] row_mask:0xf bank_mask:0xf
	v_mov_b32_dpp v239, v223 quad_perm:[1,0,3,2] row_mask:0xf bank_mask:0xf
	v_mov_b32_dpp v240, v224 quad_perm:[1,0,3,2] row_mask:0xf bank_mask:0xf
	v_mov_b32_dpp v241, v225 quad_perm:[1,0,3,2] row_mask:0xf bank_mask:0xf
	v_cndmask_b32_e64 v214, v244, v238, s[100:101]
	v_cndmask_b32_e64 v218, v238, v90, s[100:101]
	v_cndmask_b32_e64 v215, v245, v239, s[100:101]
	v_cndmask_b32_e64 v219, v239, v91, s[100:101]
	v_cndmask_b32_e64 v216, v246, v240, s[100:101]
	v_cndmask_b32_e64 v220, v240, v92, s[100:101]
	v_cndmask_b32_e64 v217, v247, v241, s[100:101]
	v_cndmask_b32_e64 v221, v241, v93, s[100:101]
	v_lshl_add_u64 v[226:227], v[126:127], 0, v[242:243]
	global_store_dwordx4 v[226:227], v[214:217], off offset:-3584
	global_store_dwordx4 v[226:227], v[218:221], off offset:512
	global_load_dwordx4 v[90:93], v[112:113], off
	s_nop 0
	v_lshl_add_u64 v[226:227], v[110:111], 0, v[242:243]
	global_load_dwordx4 v[214:217], v[226:227], off offset:-4096
	global_load_dwordx4 v[218:221], v[226:227], off
	s_waitcnt vmcnt(0)
	v_cndmask_b32_e64 v222, v218, v214, s[100:101]
	v_cndmask_b32_e64 v223, v219, v215, s[100:101]
	v_cndmask_b32_e64 v224, v220, v216, s[100:101]
	v_cndmask_b32_e64 v225, v221, v217, s[100:101]
	v_mov_b32_dpp v238, v222 quad_perm:[1,0,3,2] row_mask:0xf bank_mask:0xf
	v_mov_b32_dpp v239, v223 quad_perm:[1,0,3,2] row_mask:0xf bank_mask:0xf
	v_mov_b32_dpp v240, v224 quad_perm:[1,0,3,2] row_mask:0xf bank_mask:0xf
	v_mov_b32_dpp v241, v225 quad_perm:[1,0,3,2] row_mask:0xf bank_mask:0xf
	v_cndmask_b32_e64 v102, v214, v238, s[100:101]
	v_cndmask_b32_e64 v106, v238, v218, s[100:101]
	v_cndmask_b32_e64 v103, v215, v239, s[100:101]
	v_cndmask_b32_e64 v107, v239, v219, s[100:101]
	v_cndmask_b32_e64 v104, v216, v240, s[100:101]
	v_cndmask_b32_e64 v108, v240, v220, s[100:101]
	v_cndmask_b32_e64 v105, v217, v241, s[100:101]
	v_cndmask_b32_e64 v109, v241, v221, s[100:101]
	v_pk_fma_f32 v[92:93], v[100:101], v[92:93], v[104:105]
	v_pk_fma_f32 v[90:91], v[98:99], v[90:91], v[102:103]
	v_mov_b32_e32 v244, v90
	v_mov_b32_e32 v245, v91
	v_mov_b32_e32 v246, v92
	v_mov_b32_e32 v247, v93
	global_load_dwordx4 v[90:93], v[112:113], off offset:16
	s_waitcnt vmcnt(0)
	v_pk_fma_f32 v[92:93], v[96:97], v[92:93], v[108:109]
	v_pk_fma_f32 v[90:91], v[94:95], v[90:91], v[106:107]
	v_cndmask_b32_e64 v222, v90, v244, s[100:101]
	v_cndmask_b32_e64 v223, v91, v245, s[100:101]
	v_cndmask_b32_e64 v224, v92, v246, s[100:101]
	v_cndmask_b32_e64 v225, v93, v247, s[100:101]
	v_mov_b32_dpp v238, v222 quad_perm:[1,0,3,2] row_mask:0xf bank_mask:0xf
	v_mov_b32_dpp v239, v223 quad_perm:[1,0,3,2] row_mask:0xf bank_mask:0xf
	v_mov_b32_dpp v240, v224 quad_perm:[1,0,3,2] row_mask:0xf bank_mask:0xf
	v_mov_b32_dpp v241, v225 quad_perm:[1,0,3,2] row_mask:0xf bank_mask:0xf
	v_cndmask_b32_e64 v214, v244, v238, s[100:101]
	v_cndmask_b32_e64 v218, v238, v90, s[100:101]
	v_cndmask_b32_e64 v215, v245, v239, s[100:101]
	v_cndmask_b32_e64 v219, v239, v91, s[100:101]
	v_cndmask_b32_e64 v216, v246, v240, s[100:101]
	v_cndmask_b32_e64 v220, v240, v92, s[100:101]
	v_cndmask_b32_e64 v217, v247, v241, s[100:101]
	v_cndmask_b32_e64 v221, v241, v93, s[100:101]
	v_lshl_add_u64 v[226:227], v[110:111], 0, v[242:243]
	global_store_dwordx4 v[226:227], v[214:217], off offset:-4096
	global_store_dwordx4 v[226:227], v[218:221], off
	global_load_dwordx4 v[90:93], v[112:113], off offset:512
	s_nop 0
	v_lshl_add_u64 v[226:227], v[110:111], 0, v[242:243]
	global_load_dwordx4 v[214:217], v[226:227], off offset:-3584
	global_load_dwordx4 v[218:221], v[226:227], off offset:512
	s_waitcnt vmcnt(0)
	v_cndmask_b32_e64 v222, v218, v214, s[100:101]
	v_cndmask_b32_e64 v223, v219, v215, s[100:101]
	v_cndmask_b32_e64 v224, v220, v216, s[100:101]
	v_cndmask_b32_e64 v225, v221, v217, s[100:101]
	v_mov_b32_dpp v238, v222 quad_perm:[1,0,3,2] row_mask:0xf bank_mask:0xf
	v_mov_b32_dpp v239, v223 quad_perm:[1,0,3,2] row_mask:0xf bank_mask:0xf
	v_mov_b32_dpp v240, v224 quad_perm:[1,0,3,2] row_mask:0xf bank_mask:0xf
	v_mov_b32_dpp v241, v225 quad_perm:[1,0,3,2] row_mask:0xf bank_mask:0xf
	v_cndmask_b32_e64 v94, v214, v238, s[100:101]
	v_cndmask_b32_e64 v98, v238, v218, s[100:101]
	v_cndmask_b32_e64 v95, v215, v239, s[100:101]
	v_cndmask_b32_e64 v99, v239, v219, s[100:101]
	v_cndmask_b32_e64 v96, v216, v240, s[100:101]
	v_cndmask_b32_e64 v100, v240, v220, s[100:101]
	v_cndmask_b32_e64 v97, v217, v241, s[100:101]
	v_cndmask_b32_e64 v101, v241, v221, s[100:101]
	v_pk_fma_f32 v[88:89], v[88:89], v[92:93], v[96:97]
	v_pk_fma_f32 v[86:87], v[86:87], v[90:91], v[94:95]
	v_mov_b32_e32 v244, v86
	v_mov_b32_e32 v245, v87
	v_mov_b32_e32 v246, v88
	v_mov_b32_e32 v247, v89
	global_load_dwordx4 v[86:89], v[112:113], off offset:528
	v_add_u32_e32 v90, 48, v151
	v_min_i32_e32 v91, 0x10000, v90
	v_add_u32_e32 v92, 0xffff0030, v151
	v_ashrrev_i32_e32 v93, 31, v90
	v_ashrrev_i32_e32 v94, 13, v91
	v_cmp_gt_i32_e32 vcc, s33, v90
	v_mul_i32_i24_e32 v94, 0x1800, v94
	v_ashrrev_i32_e32 v95, 31, v94
	v_cndmask_b32_e32 v91, 0, v93, vcc
	v_cndmask_b32_e32 v90, v92, v90, vcc
	v_cndmask_b32_e32 v93, v146, v147, vcc
	v_cndmask_b32_e32 v92, v148, v149, vcc
	v_lshlrev_b64 v[90:91], 12, v[90:91]
	v_lshl_add_u64 v[90:91], v[92:93], 0, v[90:91]
	v_lshl_add_u64 v[92:93], v[94:95], 2, s[20:21]
	v_lshl_add_u64 v[96:97], v[92:93], 0, v[140:141]
	v_lshl_add_u64 v[94:95], v[90:91], 0, v[140:141]
	s_waitcnt vmcnt(0)
;     __device__ __forceinline__ void operator()(const f32x4 (&acc)[2][2][4][2], const pg8::Unit& u, int wr, int wc, int fr, int fq) const {
;     ...
;                 const int R = rowbase + u.pm * 256 + ai * 128 + wr * 64 + m * 16 + fr;
;                 const bool islat = R < TL; const int mrow = islat ? (R >> 13) : 8;
;                 const float* src = islat ? rin_l + (size_t)R * DM : rin_c + (size_t)(R - TL) * DM;
;                 float* dst = islat ? rout_l + (size_t)R * DM : rout_c + (size_t)(R - TL) * DM;
;                 const float* gp = gate + (size_t)mrow * MODW;
; #pragma unroll
;                 for (int bj = 0; bj < 2; ++bj)
; #pragma unroll
;                     for (int n = 0; n < 2; ++n) { const int c = u.pn * 256 + bj * 128 + wc * 32 + 8 * fq + 4 * n;
;                         const f32x4 g4 = *(const f32x4*)(gp + c), x4 = *(const f32x4*)(src + c);
;                         *(f32x4*)(dst + c) = x4 + g4 * acc[ai][bj][m][n]; } }
	v_pk_fma_f32 v[76:77], v[76:77], v[88:89], v[100:101]
	v_pk_fma_f32 v[74:75], v[74:75], v[86:87], v[98:99]
	v_cndmask_b32_e64 v222, v74, v244, s[100:101]
	v_cndmask_b32_e64 v223, v75, v245, s[100:101]
	v_cndmask_b32_e64 v224, v76, v246, s[100:101]
	v_cndmask_b32_e64 v225, v77, v247, s[100:101]
	v_mov_b32_dpp v238, v222 quad_perm:[1,0,3,2] row_mask:0xf bank_mask:0xf
	v_mov_b32_dpp v239, v223 quad_perm:[1,0,3,2] row_mask:0xf bank_mask:0xf
	v_mov_b32_dpp v240, v224 quad_perm:[1,0,3,2] row_mask:0xf bank_mask:0xf
	v_mov_b32_dpp v241, v225 quad_perm:[1,0,3,2] row_mask:0xf bank_mask:0xf
	v_cndmask_b32_e64 v214, v244, v238, s[100:101]
	v_cndmask_b32_e64 v218, v238, v74, s[100:101]
	v_cndmask_b32_e64 v215, v245, v239, s[100:101]
	v_cndmask_b32_e64 v219, v239, v75, s[100:101]
	v_cndmask_b32_e64 v216, v246, v240, s[100:101]
	v_cndmask_b32_e64 v220, v240, v76, s[100:101]
	v_cndmask_b32_e64 v217, v247, v241, s[100:101]
	v_cndmask_b32_e64 v221, v241, v77, s[100:101]
	v_lshl_add_u64 v[226:227], v[110:111], 0, v[242:243]
	global_store_dwordx4 v[226:227], v[214:217], off offset:-3584
	global_store_dwordx4 v[226:227], v[218:221], off offset:512
	global_load_dwordx4 v[74:77], v[96:97], off
	s_nop 0
	v_lshl_add_u64 v[226:227], v[94:95], 0, v[242:243]
	global_load_dwordx4 v[214:217], v[226:227], off offset:-4096
	global_load_dwordx4 v[218:221], v[226:227], off
	s_waitcnt vmcnt(0)
	v_cndmask_b32_e64 v222, v218, v214, s[100:101]
	v_cndmask_b32_e64 v223, v219, v215, s[100:101]
	v_cndmask_b32_e64 v224, v220, v216, s[100:101]
	v_cndmask_b32_e64 v225, v221, v217, s[100:101]
	v_mov_b32_dpp v238, v222 quad_perm:[1,0,3,2] row_mask:0xf bank_mask:0xf
	v_mov_b32_dpp v239, v223 quad_perm:[1,0,3,2] row_mask:0xf bank_mask:0xf
	v_mov_b32_dpp v240, v224 quad_perm:[1,0,3,2] row_mask:0xf bank_mask:0xf
	v_mov_b32_dpp v241, v225 quad_perm:[1,0,3,2] row_mask:0xf bank_mask:0xf
	v_cndmask_b32_e64 v86, v214, v238, s[100:101]
	v_cndmask_b32_e64 v90, v238, v218, s[100:101]
	v_cndmask_b32_e64 v87, v215, v239, s[100:101]
	v_cndmask_b32_e64 v91, v239, v219, s[100:101]
	v_cndmask_b32_e64 v88, v216, v240, s[100:101]
	v_cndmask_b32_e64 v92, v240, v220, s[100:101]
	v_cndmask_b32_e64 v89, v217, v241, s[100:101]
	v_cndmask_b32_e64 v93, v241, v221, s[100:101]
	v_pk_fma_f32 v[76:77], v[84:85], v[76:77], v[88:89]
	v_pk_fma_f32 v[74:75], v[82:83], v[74:75], v[86:87]
	v_mov_b32_e32 v244, v74
	v_mov_b32_e32 v245, v75
	v_mov_b32_e32 v246, v76
	v_mov_b32_e32 v247, v77
	global_load_dwordx4 v[74:77], v[96:97], off offset:16
	s_waitcnt vmcnt(0)
	v_pk_fma_f32 v[76:77], v[80:81], v[76:77], v[92:93]
	v_pk_fma_f32 v[74:75], v[78:79], v[74:75], v[90:91]
	v_cndmask_b32_e64 v222, v74, v244, s[100:101]
	v_cndmask_b32_e64 v223, v75, v245, s[100:101]
	v_cndmask_b32_e64 v224, v76, v246, s[100:101]
	v_cndmask_b32_e64 v225, v77, v247, s[100:101]
	v_mov_b32_dpp v238, v222 quad_perm:[1,0,3,2] row_mask:0xf bank_mask:0xf
	v_mov_b32_dpp v239, v223 quad_perm:[1,0,3,2] row_mask:0xf bank_mask:0xf
	v_mov_b32_dpp v240, v224 quad_perm:[1,0,3,2] row_mask:0xf bank_mask:0xf
	v_mov_b32_dpp v241, v225 quad_perm:[1,0,3,2] row_mask:0xf bank_mask:0xf
	v_cndmask_b32_e64 v214, v244, v238, s[100:101]
	v_cndmask_b32_e64 v218, v238, v74, s[100:101]
	v_cndmask_b32_e64 v215, v245, v239, s[100:101]
	v_cndmask_b32_e64 v219, v239, v75, s[100:101]
	v_cndmask_b32_e64 v216, v246, v240, s[100:101]
	v_cndmask_b32_e64 v220, v240, v76, s[100:101]
	v_cndmask_b32_e64 v217, v247, v241, s[100:101]
	v_cndmask_b32_e64 v221, v241, v77, s[100:101]
	v_lshl_add_u64 v[226:227], v[94:95], 0, v[242:243]
	global_store_dwordx4 v[226:227], v[214:217], off offset:-4096
	global_store_dwordx4 v[226:227], v[218:221], off
	global_load_dwordx4 v[74:77], v[96:97], off offset:512
	s_nop 0
	v_lshl_add_u64 v[226:227], v[94:95], 0, v[242:243]
	global_load_dwordx4 v[214:217], v[226:227], off offset:-3584
	global_load_dwordx4 v[218:221], v[226:227], off offset:512
	s_waitcnt vmcnt(0)
	v_cndmask_b32_e64 v222, v218, v214, s[100:101]
	v_cndmask_b32_e64 v223, v219, v215, s[100:101]
	v_cndmask_b32_e64 v224, v220, v216, s[100:101]
	v_cndmask_b32_e64 v225, v221, v217, s[100:101]
	v_mov_b32_dpp v238, v222 quad_perm:[1,0,3,2] row_mask:0xf bank_mask:0xf
	v_mov_b32_dpp v239, v223 quad_perm:[1,0,3,2] row_mask:0xf bank_mask:0xf
	v_mov_b32_dpp v240, v224 quad_perm:[1,0,3,2] row_mask:0xf bank_mask:0xf
	v_mov_b32_dpp v241, v225 quad_perm:[1,0,3,2] row_mask:0xf bank_mask:0xf
	v_cndmask_b32_e64 v78, v214, v238, s[100:101]
	v_cndmask_b32_e64 v82, v238, v218, s[100:101]
	v_cndmask_b32_e64 v79, v215, v239, s[100:101]
	v_cndmask_b32_e64 v83, v239, v219, s[100:101]
	v_cndmask_b32_e64 v80, v216, v240, s[100:101]
	v_cndmask_b32_e64 v84, v240, v220, s[100:101]
	v_cndmask_b32_e64 v81, v217, v241, s[100:101]
	v_cndmask_b32_e64 v85, v241, v221, s[100:101]
	v_pk_fma_f32 v[72:73], v[72:73], v[76:77], v[80:81]
	v_pk_fma_f32 v[70:71], v[70:71], v[74:75], v[78:79]
	v_mov_b32_e32 v244, v70
	v_mov_b32_e32 v245, v71
	v_mov_b32_e32 v246, v72
	v_mov_b32_e32 v247, v73
	global_load_dwordx4 v[70:73], v[96:97], off offset:528
	v_add_u32_e32 v74, s59, v150
	v_min_i32_e32 v75, 0x10000, v74
	v_ashrrev_i32_e32 v76, 31, v74
	v_add_u32_e32 v77, 0xffff0000, v74
	v_ashrrev_i32_e32 v78, 13, v75
	v_cmp_gt_i32_e32 vcc, s33, v74
	v_mul_i32_i24_e32 v78, 0x1800, v78
	v_ashrrev_i32_e32 v79, 31, v78
	v_cndmask_b32_e32 v75, 0, v76, vcc
	v_cndmask_b32_e32 v74, v77, v74, vcc
	v_cndmask_b32_e32 v77, v146, v147, vcc
	v_cndmask_b32_e32 v76, v148, v149, vcc
	v_lshlrev_b64 v[74:75], 12, v[74:75]
	v_lshl_add_u64 v[74:75], v[76:77], 0, v[74:75]
	v_lshl_add_u64 v[76:77], v[78:79], 2, s[20:21]
	v_lshl_add_u64 v[80:81], v[76:77], 0, v[140:141]
	v_lshl_add_u64 v[78:79], v[74:75], 0, v[140:141]
	s_waitcnt vmcnt(0)
;     __device__ __forceinline__ void operator()(const f32x4 (&acc)[2][2][4][2], const pg8::Unit& u, int wr, int wc, int fr, int fq) const {
;     ...
;                 const int R = rowbase + u.pm * 256 + ai * 128 + wr * 64 + m * 16 + fr;
;                 const bool islat = R < TL; const int mrow = islat ? (R >> 13) : 8;
;                 const float* src = islat ? rin_l + (size_t)R * DM : rin_c + (size_t)(R - TL) * DM;
;                 float* dst = islat ? rout_l + (size_t)R * DM : rout_c + (size_t)(R - TL) * DM;
;                 const float* gp = gate + (size_t)mrow * MODW;
; #pragma unroll
;                 for (int bj = 0; bj < 2; ++bj)
; #pragma unroll
;                     for (int n = 0; n < 2; ++n) { const int c = u.pn * 256 + bj * 128 + wc * 32 + 8 * fq + 4 * n;
;                         const f32x4 g4 = *(const f32x4*)(gp + c), x4 = *(const f32x4*)(src + c);
;                         *(f32x4*)(dst + c) = x4 + g4 * acc[ai][bj][m][n]; } }
	v_pk_fma_f32 v[68:69], v[68:69], v[72:73], v[84:85]
	v_pk_fma_f32 v[66:67], v[66:67], v[70:71], v[82:83]
	v_cndmask_b32_e64 v222, v66, v244, s[100:101]
	v_cndmask_b32_e64 v223, v67, v245, s[100:101]
	v_cndmask_b32_e64 v224, v68, v246, s[100:101]
	v_cndmask_b32_e64 v225, v69, v247, s[100:101]
	v_mov_b32_dpp v238, v222 quad_perm:[1,0,3,2] row_mask:0xf bank_mask:0xf
	v_mov_b32_dpp v239, v223 quad_perm:[1,0,3,2] row_mask:0xf bank_mask:0xf
	v_mov_b32_dpp v240, v224 quad_perm:[1,0,3,2] row_mask:0xf bank_mask:0xf
	v_mov_b32_dpp v241, v225 quad_perm:[1,0,3,2] row_mask:0xf bank_mask:0xf
	v_cndmask_b32_e64 v214, v244, v238, s[100:101]
	v_cndmask_b32_e64 v218, v238, v66, s[100:101]
	v_cndmask_b32_e64 v215, v245, v239, s[100:101]
	v_cndmask_b32_e64 v219, v239, v67, s[100:101]
	v_cndmask_b32_e64 v216, v246, v240, s[100:101]
	v_cndmask_b32_e64 v220, v240, v68, s[100:101]
	v_cndmask_b32_e64 v217, v247, v241, s[100:101]
	v_cndmask_b32_e64 v221, v241, v69, s[100:101]
	v_lshl_add_u64 v[226:227], v[94:95], 0, v[242:243]
	global_store_dwordx4 v[226:227], v[214:217], off offset:-3584
	global_store_dwordx4 v[226:227], v[218:221], off offset:512
	global_load_dwordx4 v[66:69], v[80:81], off
	s_nop 0
	v_lshl_add_u64 v[226:227], v[78:79], 0, v[242:243]
	global_load_dwordx4 v[214:217], v[226:227], off offset:-4096
	global_load_dwordx4 v[218:221], v[226:227], off
	s_waitcnt vmcnt(0)
	v_cndmask_b32_e64 v222, v218, v214, s[100:101]
	v_cndmask_b32_e64 v223, v219, v215, s[100:101]
	v_cndmask_b32_e64 v224, v220, v216, s[100:101]
	v_cndmask_b32_e64 v225, v221, v217, s[100:101]
	v_mov_b32_dpp v238, v222 quad_perm:[1,0,3,2] row_mask:0xf bank_mask:0xf
	v_mov_b32_dpp v239, v223 quad_perm:[1,0,3,2] row_mask:0xf bank_mask:0xf
	v_mov_b32_dpp v240, v224 quad_perm:[1,0,3,2] row_mask:0xf bank_mask:0xf
	v_mov_b32_dpp v241, v225 quad_perm:[1,0,3,2] row_mask:0xf bank_mask:0xf
	v_cndmask_b32_e64 v70, v214, v238, s[100:101]
	v_cndmask_b32_e64 v74, v238, v218, s[100:101]
	v_cndmask_b32_e64 v71, v215, v239, s[100:101]
	v_cndmask_b32_e64 v75, v239, v219, s[100:101]
	v_cndmask_b32_e64 v72, v216, v240, s[100:101]
	v_cndmask_b32_e64 v76, v240, v220, s[100:101]
	v_cndmask_b32_e64 v73, v217, v241, s[100:101]
	v_cndmask_b32_e64 v77, v241, v221, s[100:101]
	v_pk_fma_f32 v[64:65], v[64:65], v[68:69], v[72:73]
	v_pk_fma_f32 v[62:63], v[62:63], v[66:67], v[70:71]
	v_mov_b32_e32 v244, v62
	v_mov_b32_e32 v245, v63
	v_mov_b32_e32 v246, v64
	v_mov_b32_e32 v247, v65
	global_load_dwordx4 v[62:65], v[80:81], off offset:16
	s_waitcnt vmcnt(0)
	v_pk_fma_f32 v[60:61], v[60:61], v[64:65], v[76:77]
	v_pk_fma_f32 v[58:59], v[58:59], v[62:63], v[74:75]
	v_cndmask_b32_e64 v222, v58, v244, s[100:101]
	v_cndmask_b32_e64 v223, v59, v245, s[100:101]
	v_cndmask_b32_e64 v224, v60, v246, s[100:101]
	v_cndmask_b32_e64 v225, v61, v247, s[100:101]
	v_mov_b32_dpp v238, v222 quad_perm:[1,0,3,2] row_mask:0xf bank_mask:0xf
	v_mov_b32_dpp v239, v223 quad_perm:[1,0,3,2] row_mask:0xf bank_mask:0xf
	v_mov_b32_dpp v240, v224 quad_perm:[1,0,3,2] row_mask:0xf bank_mask:0xf
	v_mov_b32_dpp v241, v225 quad_perm:[1,0,3,2] row_mask:0xf bank_mask:0xf
	v_cndmask_b32_e64 v214, v244, v238, s[100:101]
	v_cndmask_b32_e64 v218, v238, v58, s[100:101]
	v_cndmask_b32_e64 v215, v245, v239, s[100:101]
	v_cndmask_b32_e64 v219, v239, v59, s[100:101]
	v_cndmask_b32_e64 v216, v246, v240, s[100:101]
	v_cndmask_b32_e64 v220, v240, v60, s[100:101]
	v_cndmask_b32_e64 v217, v247, v241, s[100:101]
	v_cndmask_b32_e64 v221, v241, v61, s[100:101]
	v_lshl_add_u64 v[226:227], v[78:79], 0, v[242:243]
	global_store_dwordx4 v[226:227], v[214:217], off offset:-4096
	global_store_dwordx4 v[226:227], v[218:221], off
	global_load_dwordx4 v[58:61], v[80:81], off offset:512
	s_nop 0
	v_lshl_add_u64 v[226:227], v[78:79], 0, v[242:243]
	global_load_dwordx4 v[214:217], v[226:227], off offset:-3584
	global_load_dwordx4 v[218:221], v[226:227], off offset:512
	s_waitcnt vmcnt(0)
	v_cndmask_b32_e64 v222, v218, v214, s[100:101]
	v_cndmask_b32_e64 v223, v219, v215, s[100:101]
	v_cndmask_b32_e64 v224, v220, v216, s[100:101]
	v_cndmask_b32_e64 v225, v221, v217, s[100:101]
	v_mov_b32_dpp v238, v222 quad_perm:[1,0,3,2] row_mask:0xf bank_mask:0xf
	v_mov_b32_dpp v239, v223 quad_perm:[1,0,3,2] row_mask:0xf bank_mask:0xf
	v_mov_b32_dpp v240, v224 quad_perm:[1,0,3,2] row_mask:0xf bank_mask:0xf
	v_mov_b32_dpp v241, v225 quad_perm:[1,0,3,2] row_mask:0xf bank_mask:0xf
	v_cndmask_b32_e64 v62, v214, v238, s[100:101]
	v_cndmask_b32_e64 v66, v238, v218, s[100:101]
	v_cndmask_b32_e64 v63, v215, v239, s[100:101]
	v_cndmask_b32_e64 v67, v239, v219, s[100:101]
	v_cndmask_b32_e64 v64, v216, v240, s[100:101]
	v_cndmask_b32_e64 v68, v240, v220, s[100:101]
	v_cndmask_b32_e64 v65, v217, v241, s[100:101]
	v_cndmask_b32_e64 v69, v241, v221, s[100:101]
	v_pk_fma_f32 v[56:57], v[56:57], v[60:61], v[64:65]
	v_pk_fma_f32 v[54:55], v[54:55], v[58:59], v[62:63]
	v_mov_b32_e32 v244, v54
	v_mov_b32_e32 v245, v55
	v_mov_b32_e32 v246, v56
	v_mov_b32_e32 v247, v57
	global_load_dwordx4 v[54:57], v[80:81], off offset:528
	v_add_u32_e32 v58, s60, v150
	v_min_i32_e32 v59, 0x10000, v58
	v_ashrrev_i32_e32 v60, 31, v58
	v_add_u32_e32 v61, 0xffff0000, v58
	v_ashrrev_i32_e32 v62, 13, v59
	v_cmp_gt_i32_e32 vcc, s33, v58
	v_mul_i32_i24_e32 v62, 0x1800, v62
	v_ashrrev_i32_e32 v63, 31, v62
	v_cndmask_b32_e32 v59, 0, v60, vcc
	v_cndmask_b32_e32 v58, v61, v58, vcc
	v_cndmask_b32_e32 v61, v146, v147, vcc
	v_cndmask_b32_e32 v60, v148, v149, vcc
	v_lshlrev_b64 v[58:59], 12, v[58:59]
	v_lshl_add_u64 v[58:59], v[60:61], 0, v[58:59]
	v_lshl_add_u64 v[60:61], v[62:63], 2, s[20:21]
	v_lshl_add_u64 v[64:65], v[60:61], 0, v[140:141]
	v_lshl_add_u64 v[62:63], v[58:59], 0, v[140:141]
	s_waitcnt vmcnt(0)
;     __device__ __forceinline__ void operator()(const f32x4 (&acc)[2][2][4][2], const pg8::Unit& u, int wr, int wc, int fr, int fq) const {
;     ...
;                 const int R = rowbase + u.pm * 256 + ai * 128 + wr * 64 + m * 16 + fr;
;                 const bool islat = R < TL; const int mrow = islat ? (R >> 13) : 8;
;                 const float* src = islat ? rin_l + (size_t)R * DM : rin_c + (size_t)(R - TL) * DM;
;                 float* dst = islat ? rout_l + (size_t)R * DM : rout_c + (size_t)(R - TL) * DM;
;                 const float* gp = gate + (size_t)mrow * MODW;
; #pragma unroll
;                 for (int bj = 0; bj < 2; ++bj)
; #pragma unroll
;                     for (int n = 0; n < 2; ++n) { const int c = u.pn * 256 + bj * 128 + wc * 32 + 8 * fq + 4 * n;
;                         const f32x4 g4 = *(const f32x4*)(gp + c), x4 = *(const f32x4*)(src + c);
;                         *(f32x4*)(dst + c) = x4 + g4 * acc[ai][bj][m][n]; } }
	v_pk_fma_f32 v[44:45], v[44:45], v[56:57], v[68:69]
	v_pk_fma_f32 v[42:43], v[42:43], v[54:55], v[66:67]
	v_cndmask_b32_e64 v222, v42, v244, s[100:101]
	v_cndmask_b32_e64 v223, v43, v245, s[100:101]
	v_cndmask_b32_e64 v224, v44, v246, s[100:101]
	v_cndmask_b32_e64 v225, v45, v247, s[100:101]
	v_mov_b32_dpp v238, v222 quad_perm:[1,0,3,2] row_mask:0xf bank_mask:0xf
	v_mov_b32_dpp v239, v223 quad_perm:[1,0,3,2] row_mask:0xf bank_mask:0xf
	v_mov_b32_dpp v240, v224 quad_perm:[1,0,3,2] row_mask:0xf bank_mask:0xf
	v_mov_b32_dpp v241, v225 quad_perm:[1,0,3,2] row_mask:0xf bank_mask:0xf
	v_cndmask_b32_e64 v214, v244, v238, s[100:101]
	v_cndmask_b32_e64 v218, v238, v42, s[100:101]
	v_cndmask_b32_e64 v215, v245, v239, s[100:101]
	v_cndmask_b32_e64 v219, v239, v43, s[100:101]
	v_cndmask_b32_e64 v216, v246, v240, s[100:101]
	v_cndmask_b32_e64 v220, v240, v44, s[100:101]
	v_cndmask_b32_e64 v217, v247, v241, s[100:101]
	v_cndmask_b32_e64 v221, v241, v45, s[100:101]
	v_lshl_add_u64 v[226:227], v[78:79], 0, v[242:243]
	global_store_dwordx4 v[226:227], v[214:217], off offset:-3584
	global_store_dwordx4 v[226:227], v[218:221], off offset:512
	global_load_dwordx4 v[42:45], v[64:65], off
	s_nop 0
	v_lshl_add_u64 v[226:227], v[62:63], 0, v[242:243]
	global_load_dwordx4 v[214:217], v[226:227], off offset:-4096
	global_load_dwordx4 v[218:221], v[226:227], off
	s_waitcnt vmcnt(0)
	v_cndmask_b32_e64 v222, v218, v214, s[100:101]
	v_cndmask_b32_e64 v223, v219, v215, s[100:101]
	v_cndmask_b32_e64 v224, v220, v216, s[100:101]
	v_cndmask_b32_e64 v225, v221, v217, s[100:101]
	v_mov_b32_dpp v238, v222 quad_perm:[1,0,3,2] row_mask:0xf bank_mask:0xf
	v_mov_b32_dpp v239, v223 quad_perm:[1,0,3,2] row_mask:0xf bank_mask:0xf
	v_mov_b32_dpp v240, v224 quad_perm:[1,0,3,2] row_mask:0xf bank_mask:0xf
	v_mov_b32_dpp v241, v225 quad_perm:[1,0,3,2] row_mask:0xf bank_mask:0xf
	v_cndmask_b32_e64 v54, v214, v238, s[100:101]
	v_cndmask_b32_e64 v58, v238, v218, s[100:101]
	v_cndmask_b32_e64 v55, v215, v239, s[100:101]
	v_cndmask_b32_e64 v59, v239, v219, s[100:101]
	v_cndmask_b32_e64 v56, v216, v240, s[100:101]
	v_cndmask_b32_e64 v60, v240, v220, s[100:101]
	v_cndmask_b32_e64 v57, v217, v241, s[100:101]
	v_cndmask_b32_e64 v61, v241, v221, s[100:101]
	v_pk_fma_f32 v[44:45], v[52:53], v[44:45], v[56:57]
	v_pk_fma_f32 v[42:43], v[50:51], v[42:43], v[54:55]
	v_mov_b32_e32 v244, v42
	v_mov_b32_e32 v245, v43
	v_mov_b32_e32 v246, v44
	v_mov_b32_e32 v247, v45
	global_load_dwordx4 v[42:45], v[64:65], off offset:16
	s_waitcnt vmcnt(0)
	v_pk_fma_f32 v[44:45], v[48:49], v[44:45], v[60:61]
	v_pk_fma_f32 v[42:43], v[46:47], v[42:43], v[58:59]
	v_cndmask_b32_e64 v222, v42, v244, s[100:101]
	v_cndmask_b32_e64 v223, v43, v245, s[100:101]
	v_cndmask_b32_e64 v224, v44, v246, s[100:101]
	v_cndmask_b32_e64 v225, v45, v247, s[100:101]
	v_mov_b32_dpp v238, v222 quad_perm:[1,0,3,2] row_mask:0xf bank_mask:0xf
	v_mov_b32_dpp v239, v223 quad_perm:[1,0,3,2] row_mask:0xf bank_mask:0xf
	v_mov_b32_dpp v240, v224 quad_perm:[1,0,3,2] row_mask:0xf bank_mask:0xf
	v_mov_b32_dpp v241, v225 quad_perm:[1,0,3,2] row_mask:0xf bank_mask:0xf
	v_cndmask_b32_e64 v214, v244, v238, s[100:101]
	v_cndmask_b32_e64 v218, v238, v42, s[100:101]
	v_cndmask_b32_e64 v215, v245, v239, s[100:101]
	v_cndmask_b32_e64 v219, v239, v43, s[100:101]
	v_cndmask_b32_e64 v216, v246, v240, s[100:101]
	v_cndmask_b32_e64 v220, v240, v44, s[100:101]
	v_cndmask_b32_e64 v217, v247, v241, s[100:101]
	v_cndmask_b32_e64 v221, v241, v45, s[100:101]
	v_lshl_add_u64 v[226:227], v[62:63], 0, v[242:243]
	global_store_dwordx4 v[226:227], v[214:217], off offset:-4096
	global_store_dwordx4 v[226:227], v[218:221], off
	global_load_dwordx4 v[42:45], v[64:65], off offset:512
	s_nop 0
	v_lshl_add_u64 v[226:227], v[62:63], 0, v[242:243]
	global_load_dwordx4 v[214:217], v[226:227], off offset:-3584
	global_load_dwordx4 v[218:221], v[226:227], off offset:512
	s_waitcnt vmcnt(0)
	v_cndmask_b32_e64 v222, v218, v214, s[100:101]
	v_cndmask_b32_e64 v223, v219, v215, s[100:101]
	v_cndmask_b32_e64 v224, v220, v216, s[100:101]
	v_cndmask_b32_e64 v225, v221, v217, s[100:101]
	v_mov_b32_dpp v238, v222 quad_perm:[1,0,3,2] row_mask:0xf bank_mask:0xf
	v_mov_b32_dpp v239, v223 quad_perm:[1,0,3,2] row_mask:0xf bank_mask:0xf
	v_mov_b32_dpp v240, v224 quad_perm:[1,0,3,2] row_mask:0xf bank_mask:0xf
	v_mov_b32_dpp v241, v225 quad_perm:[1,0,3,2] row_mask:0xf bank_mask:0xf
	v_cndmask_b32_e64 v46, v214, v238, s[100:101]
	v_cndmask_b32_e64 v50, v238, v218, s[100:101]
	v_cndmask_b32_e64 v47, v215, v239, s[100:101]
	v_cndmask_b32_e64 v51, v239, v219, s[100:101]
	v_cndmask_b32_e64 v48, v216, v240, s[100:101]
	v_cndmask_b32_e64 v52, v240, v220, s[100:101]
	v_cndmask_b32_e64 v49, v217, v241, s[100:101]
	v_cndmask_b32_e64 v53, v241, v221, s[100:101]
	v_pk_fma_f32 v[40:41], v[40:41], v[44:45], v[48:49]
	v_pk_fma_f32 v[38:39], v[38:39], v[42:43], v[46:47]
	v_mov_b32_e32 v244, v38
	v_mov_b32_e32 v245, v39
	v_mov_b32_e32 v246, v40
	v_mov_b32_e32 v247, v41
	global_load_dwordx4 v[38:41], v[64:65], off offset:528
	v_add_u32_e32 v42, s61, v150
	v_min_i32_e32 v43, 0x10000, v42
	v_ashrrev_i32_e32 v44, 31, v42
	v_add_u32_e32 v45, 0xffff0000, v42
	v_ashrrev_i32_e32 v46, 13, v43
	v_cmp_gt_i32_e32 vcc, s33, v42
	v_mul_i32_i24_e32 v46, 0x1800, v46
	v_ashrrev_i32_e32 v47, 31, v46
	v_cndmask_b32_e32 v43, 0, v44, vcc
	v_cndmask_b32_e32 v42, v45, v42, vcc
	v_cndmask_b32_e32 v45, v146, v147, vcc
	v_cndmask_b32_e32 v44, v148, v149, vcc
	v_lshlrev_b64 v[42:43], 12, v[42:43]
	v_lshl_add_u64 v[42:43], v[44:45], 0, v[42:43]
	v_lshl_add_u64 v[44:45], v[46:47], 2, s[20:21]
	v_lshl_add_u64 v[48:49], v[44:45], 0, v[140:141]
	v_lshl_add_u64 v[46:47], v[42:43], 0, v[140:141]
	s_waitcnt vmcnt(0)
;     __device__ __forceinline__ void operator()(const f32x4 (&acc)[2][2][4][2], const pg8::Unit& u, int wr, int wc, int fr, int fq) const {
;     ...
;                 const int R = rowbase + u.pm * 256 + ai * 128 + wr * 64 + m * 16 + fr;
;                 const bool islat = R < TL; const int mrow = islat ? (R >> 13) : 8;
;                 const float* src = islat ? rin_l + (size_t)R * DM : rin_c + (size_t)(R - TL) * DM;
;                 float* dst = islat ? rout_l + (size_t)R * DM : rout_c + (size_t)(R - TL) * DM;
;                 const float* gp = gate + (size_t)mrow * MODW;
; #pragma unroll
;                 for (int bj = 0; bj < 2; ++bj)
; #pragma unroll
;                     for (int n = 0; n < 2; ++n) { const int c = u.pn * 256 + bj * 128 + wc * 32 + 8 * fq + 4 * n;
;                         const f32x4 g4 = *(const f32x4*)(gp + c), x4 = *(const f32x4*)(src + c);
;                         *(f32x4*)(dst + c) = x4 + g4 * acc[ai][bj][m][n]; } }
	v_pk_fma_f32 v[28:29], v[28:29], v[40:41], v[52:53]
	v_pk_fma_f32 v[26:27], v[26:27], v[38:39], v[50:51]
	v_cndmask_b32_e64 v222, v26, v244, s[100:101]
	v_cndmask_b32_e64 v223, v27, v245, s[100:101]
	v_cndmask_b32_e64 v224, v28, v246, s[100:101]
	v_cndmask_b32_e64 v225, v29, v247, s[100:101]
	v_mov_b32_dpp v238, v222 quad_perm:[1,0,3,2] row_mask:0xf bank_mask:0xf
	v_mov_b32_dpp v239, v223 quad_perm:[1,0,3,2] row_mask:0xf bank_mask:0xf
	v_mov_b32_dpp v240, v224 quad_perm:[1,0,3,2] row_mask:0xf bank_mask:0xf
	v_mov_b32_dpp v241, v225 quad_perm:[1,0,3,2] row_mask:0xf bank_mask:0xf
	v_cndmask_b32_e64 v214, v244, v238, s[100:101]
	v_cndmask_b32_e64 v218, v238, v26, s[100:101]
	v_cndmask_b32_e64 v215, v245, v239, s[100:101]
	v_cndmask_b32_e64 v219, v239, v27, s[100:101]
	v_cndmask_b32_e64 v216, v246, v240, s[100:101]
	v_cndmask_b32_e64 v220, v240, v28, s[100:101]
	v_cndmask_b32_e64 v217, v247, v241, s[100:101]
	v_cndmask_b32_e64 v221, v241, v29, s[100:101]
	v_lshl_add_u64 v[226:227], v[62:63], 0, v[242:243]
	global_store_dwordx4 v[226:227], v[214:217], off offset:-3584
	global_store_dwordx4 v[226:227], v[218:221], off offset:512
	global_load_dwordx4 v[26:29], v[48:49], off
	s_nop 0
	v_lshl_add_u64 v[226:227], v[46:47], 0, v[242:243]
	global_load_dwordx4 v[214:217], v[226:227], off offset:-4096
	global_load_dwordx4 v[218:221], v[226:227], off
	s_waitcnt vmcnt(0)
	v_cndmask_b32_e64 v222, v218, v214, s[100:101]
	v_cndmask_b32_e64 v223, v219, v215, s[100:101]
	v_cndmask_b32_e64 v224, v220, v216, s[100:101]
	v_cndmask_b32_e64 v225, v221, v217, s[100:101]
	v_mov_b32_dpp v238, v222 quad_perm:[1,0,3,2] row_mask:0xf bank_mask:0xf
	v_mov_b32_dpp v239, v223 quad_perm:[1,0,3,2] row_mask:0xf bank_mask:0xf
	v_mov_b32_dpp v240, v224 quad_perm:[1,0,3,2] row_mask:0xf bank_mask:0xf
	v_mov_b32_dpp v241, v225 quad_perm:[1,0,3,2] row_mask:0xf bank_mask:0xf
	v_cndmask_b32_e64 v38, v214, v238, s[100:101]
	v_cndmask_b32_e64 v42, v238, v218, s[100:101]
	v_cndmask_b32_e64 v39, v215, v239, s[100:101]
	v_cndmask_b32_e64 v43, v239, v219, s[100:101]
	v_cndmask_b32_e64 v40, v216, v240, s[100:101]
	v_cndmask_b32_e64 v44, v240, v220, s[100:101]
	v_cndmask_b32_e64 v41, v217, v241, s[100:101]
	v_cndmask_b32_e64 v45, v241, v221, s[100:101]
	v_pk_fma_f32 v[28:29], v[36:37], v[28:29], v[40:41]
	v_pk_fma_f32 v[26:27], v[34:35], v[26:27], v[38:39]
	v_mov_b32_e32 v244, v26
	v_mov_b32_e32 v245, v27
	v_mov_b32_e32 v246, v28
	v_mov_b32_e32 v247, v29
	global_load_dwordx4 v[26:29], v[48:49], off offset:16
	s_waitcnt vmcnt(0)
	v_pk_fma_f32 v[28:29], v[32:33], v[28:29], v[44:45]
	v_pk_fma_f32 v[26:27], v[30:31], v[26:27], v[42:43]
	v_cndmask_b32_e64 v222, v26, v244, s[100:101]
	v_cndmask_b32_e64 v223, v27, v245, s[100:101]
	v_cndmask_b32_e64 v224, v28, v246, s[100:101]
	v_cndmask_b32_e64 v225, v29, v247, s[100:101]
	v_mov_b32_dpp v238, v222 quad_perm:[1,0,3,2] row_mask:0xf bank_mask:0xf
	v_mov_b32_dpp v239, v223 quad_perm:[1,0,3,2] row_mask:0xf bank_mask:0xf
	v_mov_b32_dpp v240, v224 quad_perm:[1,0,3,2] row_mask:0xf bank_mask:0xf
	v_mov_b32_dpp v241, v225 quad_perm:[1,0,3,2] row_mask:0xf bank_mask:0xf
	v_cndmask_b32_e64 v214, v244, v238, s[100:101]
	v_cndmask_b32_e64 v218, v238, v26, s[100:101]
	v_cndmask_b32_e64 v215, v245, v239, s[100:101]
	v_cndmask_b32_e64 v219, v239, v27, s[100:101]
	v_cndmask_b32_e64 v216, v246, v240, s[100:101]
	v_cndmask_b32_e64 v220, v240, v28, s[100:101]
	v_cndmask_b32_e64 v217, v247, v241, s[100:101]
	v_cndmask_b32_e64 v221, v241, v29, s[100:101]
	v_lshl_add_u64 v[226:227], v[46:47], 0, v[242:243]
	global_store_dwordx4 v[226:227], v[214:217], off offset:-4096
	global_store_dwordx4 v[226:227], v[218:221], off
	global_load_dwordx4 v[26:29], v[48:49], off offset:512
	s_nop 0
	v_lshl_add_u64 v[226:227], v[46:47], 0, v[242:243]
	global_load_dwordx4 v[214:217], v[226:227], off offset:-3584
	global_load_dwordx4 v[218:221], v[226:227], off offset:512
	s_waitcnt vmcnt(0)
	v_cndmask_b32_e64 v222, v218, v214, s[100:101]
	v_cndmask_b32_e64 v223, v219, v215, s[100:101]
	v_cndmask_b32_e64 v224, v220, v216, s[100:101]
	v_cndmask_b32_e64 v225, v221, v217, s[100:101]
	v_mov_b32_dpp v238, v222 quad_perm:[1,0,3,2] row_mask:0xf bank_mask:0xf
	v_mov_b32_dpp v239, v223 quad_perm:[1,0,3,2] row_mask:0xf bank_mask:0xf
	v_mov_b32_dpp v240, v224 quad_perm:[1,0,3,2] row_mask:0xf bank_mask:0xf
	v_mov_b32_dpp v241, v225 quad_perm:[1,0,3,2] row_mask:0xf bank_mask:0xf
	v_cndmask_b32_e64 v30, v214, v238, s[100:101]
	v_cndmask_b32_e64 v34, v238, v218, s[100:101]
	v_cndmask_b32_e64 v31, v215, v239, s[100:101]
	v_cndmask_b32_e64 v35, v239, v219, s[100:101]
	v_cndmask_b32_e64 v32, v216, v240, s[100:101]
	v_cndmask_b32_e64 v36, v240, v220, s[100:101]
	v_cndmask_b32_e64 v33, v217, v241, s[100:101]
	v_cndmask_b32_e64 v37, v241, v221, s[100:101]
	v_pk_fma_f32 v[24:25], v[24:25], v[28:29], v[32:33]
	v_pk_fma_f32 v[22:23], v[22:23], v[26:27], v[30:31]
	v_mov_b32_e32 v244, v22
	v_mov_b32_e32 v245, v23
	v_mov_b32_e32 v246, v24
	v_mov_b32_e32 v247, v25
	global_load_dwordx4 v[22:25], v[48:49], off offset:528
	v_add_u32_e32 v26, s62, v150
	v_min_i32_e32 v30, 0x10000, v26
	v_ashrrev_i32_e32 v27, 31, v26
	v_add_u32_e32 v28, 0xffff0000, v26
	v_cmp_gt_i32_e32 vcc, s33, v26
	v_ashrrev_i32_e32 v30, 13, v30
	v_mul_i32_i24_e32 v30, 0x1800, v30
	v_cndmask_b32_e32 v27, 0, v27, vcc
	v_cndmask_b32_e32 v26, v28, v26, vcc
	v_cndmask_b32_e32 v29, v146, v147, vcc
	v_cndmask_b32_e32 v28, v148, v149, vcc
	v_lshlrev_b64 v[26:27], 12, v[26:27]
	v_ashrrev_i32_e32 v31, 31, v30
	v_lshl_add_u64 v[26:27], v[28:29], 0, v[26:27]
	v_lshl_add_u64 v[28:29], v[30:31], 2, s[20:21]
	v_lshl_add_u64 v[32:33], v[28:29], 0, v[140:141]
	v_lshl_add_u64 v[30:31], v[26:27], 0, v[140:141]
	s_and_b64 vcc, exec, s[38:39]
	s_waitcnt vmcnt(0)
; #define PG8_BAR __builtin_amdgcn_s_barrier()
; template <class Epi, class Sched, bool ALIGN_EPI = false, bool SP2 = false>
; __device__ __forceinline__ void gemm_phase(PG8_LAS unsigned char* lds, const Gemm g, const Sched& S, const Epi& E) {
;     ...
;         if (!has_next) break;
; #pragma unroll
;         for (int a = 0; a < 2; ++a)
; #pragma unroll
;             for (int b = 0; b < 2; ++b)
; #pragma unroll
;                 for (int m = 0; m < 4; ++m)
; #pragma unroll
;                     for (int n = 0; n < 2; ++n) acc[a][b][m][n] = (f32x4){0.f, 0.f, 0.f, 0.f};
;         cur = nxt; cA = nA; cB = nB; ++ui;
;         if constexpr (ALIGN_EPI) { if (wr == 1) PG8_BAR; }
;     __device__ __forceinline__ void operator()(const f32x4 (&acc)[2][2][4][2], const pg8::Unit& u, int wr, int wc, int fr, int fq) const {
;     ...
;                 const int R = rowbase + u.pm * 256 + ai * 128 + wr * 64 + m * 16 + fr;
;                 const bool islat = R < TL; const int mrow = islat ? (R >> 13) : 8;
;                 const float* src = islat ? rin_l + (size_t)R * DM : rin_c + (size_t)(R - TL) * DM;
;                 float* dst = islat ? rout_l + (size_t)R * DM : rout_c + (size_t)(R - TL) * DM;
;                 const float* gp = gate + (size_t)mrow * MODW;
; #pragma unroll
;                 for (int bj = 0; bj < 2; ++bj)
; #pragma unroll
;                     for (int n = 0; n < 2; ++n) { const int c = u.pn * 256 + bj * 128 + wc * 32 + 8 * fq + 4 * n;
;                         const f32x4 g4 = *(const f32x4*)(gp + c), x4 = *(const f32x4*)(src + c);
;                         *(f32x4*)(dst + c) = x4 + g4 * acc[ai][bj][m][n]; } }
	v_pk_fma_f32 v[12:13], v[12:13], v[24:25], v[36:37]
	v_pk_fma_f32 v[10:11], v[10:11], v[22:23], v[34:35]
	v_cndmask_b32_e64 v222, v10, v244, s[100:101]
	v_cndmask_b32_e64 v223, v11, v245, s[100:101]
	v_cndmask_b32_e64 v224, v12, v246, s[100:101]
	v_cndmask_b32_e64 v225, v13, v247, s[100:101]
	v_mov_b32_dpp v238, v222 quad_perm:[1,0,3,2] row_mask:0xf bank_mask:0xf
	v_mov_b32_dpp v239, v223 quad_perm:[1,0,3,2] row_mask:0xf bank_mask:0xf
	v_mov_b32_dpp v240, v224 quad_perm:[1,0,3,2] row_mask:0xf bank_mask:0xf
	v_mov_b32_dpp v241, v225 quad_perm:[1,0,3,2] row_mask:0xf bank_mask:0xf
	v_cndmask_b32_e64 v214, v244, v238, s[100:101]
	v_cndmask_b32_e64 v218, v238, v10, s[100:101]
	v_cndmask_b32_e64 v215, v245, v239, s[100:101]
	v_cndmask_b32_e64 v219, v239, v11, s[100:101]
	v_cndmask_b32_e64 v216, v246, v240, s[100:101]
	v_cndmask_b32_e64 v220, v240, v12, s[100:101]
	v_cndmask_b32_e64 v217, v247, v241, s[100:101]
	v_cndmask_b32_e64 v221, v241, v13, s[100:101]
	v_lshl_add_u64 v[226:227], v[46:47], 0, v[242:243]
	global_store_dwordx4 v[226:227], v[214:217], off offset:-3584
	global_store_dwordx4 v[226:227], v[218:221], off offset:512
	global_load_dwordx4 v[10:13], v[32:33], off
	s_nop 0
	v_lshl_add_u64 v[226:227], v[30:31], 0, v[242:243]
	global_load_dwordx4 v[214:217], v[226:227], off offset:-4096
	global_load_dwordx4 v[218:221], v[226:227], off
	s_waitcnt vmcnt(0)
	v_cndmask_b32_e64 v222, v218, v214, s[100:101]
	v_cndmask_b32_e64 v223, v219, v215, s[100:101]
	v_cndmask_b32_e64 v224, v220, v216, s[100:101]
	v_cndmask_b32_e64 v225, v221, v217, s[100:101]
	v_mov_b32_dpp v238, v222 quad_perm:[1,0,3,2] row_mask:0xf bank_mask:0xf
	v_mov_b32_dpp v239, v223 quad_perm:[1,0,3,2] row_mask:0xf bank_mask:0xf
	v_mov_b32_dpp v240, v224 quad_perm:[1,0,3,2] row_mask:0xf bank_mask:0xf
	v_mov_b32_dpp v241, v225 quad_perm:[1,0,3,2] row_mask:0xf bank_mask:0xf
	v_cndmask_b32_e64 v22, v214, v238, s[100:101]
	v_cndmask_b32_e64 v26, v238, v218, s[100:101]
	v_cndmask_b32_e64 v23, v215, v239, s[100:101]
	v_cndmask_b32_e64 v27, v239, v219, s[100:101]
	v_cndmask_b32_e64 v24, v216, v240, s[100:101]
	v_cndmask_b32_e64 v28, v240, v220, s[100:101]
	v_cndmask_b32_e64 v25, v217, v241, s[100:101]
	v_cndmask_b32_e64 v29, v241, v221, s[100:101]
	v_pk_fma_f32 v[12:13], v[20:21], v[12:13], v[24:25]
	v_pk_fma_f32 v[10:11], v[18:19], v[10:11], v[22:23]
	v_mov_b32_e32 v244, v10
	v_mov_b32_e32 v245, v11
	v_mov_b32_e32 v246, v12
	v_mov_b32_e32 v247, v13
	global_load_dwordx4 v[10:13], v[32:33], off offset:16
	s_waitcnt vmcnt(0)
	v_pk_fma_f32 v[12:13], v[16:17], v[12:13], v[28:29]
	v_pk_fma_f32 v[10:11], v[14:15], v[10:11], v[26:27]
	v_cndmask_b32_e64 v222, v10, v244, s[100:101]
	v_cndmask_b32_e64 v223, v11, v245, s[100:101]
	v_cndmask_b32_e64 v224, v12, v246, s[100:101]
	v_cndmask_b32_e64 v225, v13, v247, s[100:101]
	v_mov_b32_dpp v238, v222 quad_perm:[1,0,3,2] row_mask:0xf bank_mask:0xf
	v_mov_b32_dpp v239, v223 quad_perm:[1,0,3,2] row_mask:0xf bank_mask:0xf
	v_mov_b32_dpp v240, v224 quad_perm:[1,0,3,2] row_mask:0xf bank_mask:0xf
	v_mov_b32_dpp v241, v225 quad_perm:[1,0,3,2] row_mask:0xf bank_mask:0xf
	v_cndmask_b32_e64 v214, v244, v238, s[100:101]
	v_cndmask_b32_e64 v218, v238, v10, s[100:101]
	v_cndmask_b32_e64 v215, v245, v239, s[100:101]
	v_cndmask_b32_e64 v219, v239, v11, s[100:101]
	v_cndmask_b32_e64 v216, v246, v240, s[100:101]
	v_cndmask_b32_e64 v220, v240, v12, s[100:101]
	v_cndmask_b32_e64 v217, v247, v241, s[100:101]
	v_cndmask_b32_e64 v221, v241, v13, s[100:101]
	v_lshl_add_u64 v[226:227], v[30:31], 0, v[242:243]
	global_store_dwordx4 v[226:227], v[214:217], off offset:-4096
	global_store_dwordx4 v[226:227], v[218:221], off
	global_load_dwordx4 v[10:13], v[32:33], off offset:512
	s_nop 0
	v_lshl_add_u64 v[226:227], v[30:31], 0, v[242:243]
	global_load_dwordx4 v[214:217], v[226:227], off offset:-3584
	global_load_dwordx4 v[218:221], v[226:227], off offset:512
	s_waitcnt vmcnt(0)
	v_cndmask_b32_e64 v222, v218, v214, s[100:101]
	v_cndmask_b32_e64 v223, v219, v215, s[100:101]
	v_cndmask_b32_e64 v224, v220, v216, s[100:101]
	v_cndmask_b32_e64 v225, v221, v217, s[100:101]
	v_mov_b32_dpp v238, v222 quad_perm:[1,0,3,2] row_mask:0xf bank_mask:0xf
	v_mov_b32_dpp v239, v223 quad_perm:[1,0,3,2] row_mask:0xf bank_mask:0xf
	v_mov_b32_dpp v240, v224 quad_perm:[1,0,3,2] row_mask:0xf bank_mask:0xf
	v_mov_b32_dpp v241, v225 quad_perm:[1,0,3,2] row_mask:0xf bank_mask:0xf
	v_cndmask_b32_e64 v14, v214, v238, s[100:101]
	v_cndmask_b32_e64 v18, v238, v218, s[100:101]
	v_cndmask_b32_e64 v15, v215, v239, s[100:101]
	v_cndmask_b32_e64 v19, v239, v219, s[100:101]
	v_cndmask_b32_e64 v16, v216, v240, s[100:101]
	v_cndmask_b32_e64 v20, v240, v220, s[100:101]
	v_cndmask_b32_e64 v17, v217, v241, s[100:101]
	v_cndmask_b32_e64 v21, v241, v221, s[100:101]
	v_pk_fma_f32 v[8:9], v[8:9], v[12:13], v[16:17]
	v_pk_fma_f32 v[6:7], v[6:7], v[10:11], v[14:15]
	v_mov_b32_e32 v244, v6
	v_mov_b32_e32 v245, v7
	v_mov_b32_e32 v246, v8
	v_mov_b32_e32 v247, v9
	global_load_dwordx4 v[6:9], v[32:33], off offset:528
	s_waitcnt vmcnt(0)
	v_pk_fma_f32 v[4:5], v[4:5], v[8:9], v[20:21]
	v_pk_fma_f32 v[2:3], v[2:3], v[6:7], v[18:19]
	v_cndmask_b32_e64 v222, v2, v244, s[100:101]
	v_cndmask_b32_e64 v223, v3, v245, s[100:101]
	v_cndmask_b32_e64 v224, v4, v246, s[100:101]
	v_cndmask_b32_e64 v225, v5, v247, s[100:101]
	v_mov_b32_dpp v238, v222 quad_perm:[1,0,3,2] row_mask:0xf bank_mask:0xf
	v_mov_b32_dpp v239, v223 quad_perm:[1,0,3,2] row_mask:0xf bank_mask:0xf
	v_mov_b32_dpp v240, v224 quad_perm:[1,0,3,2] row_mask:0xf bank_mask:0xf
	v_mov_b32_dpp v241, v225 quad_perm:[1,0,3,2] row_mask:0xf bank_mask:0xf
	v_cndmask_b32_e64 v214, v244, v238, s[100:101]
	v_cndmask_b32_e64 v218, v238, v2, s[100:101]
	v_cndmask_b32_e64 v215, v245, v239, s[100:101]
	v_cndmask_b32_e64 v219, v239, v3, s[100:101]
	v_cndmask_b32_e64 v216, v246, v240, s[100:101]
	v_cndmask_b32_e64 v220, v240, v4, s[100:101]
	v_cndmask_b32_e64 v217, v247, v241, s[100:101]
	v_cndmask_b32_e64 v221, v241, v5, s[100:101]
	v_lshl_add_u64 v[226:227], v[30:31], 0, v[242:243]
	global_store_dwordx4 v[226:227], v[214:217], off offset:-3584
	global_store_dwordx4 v[226:227], v[218:221], off offset:512
	s_cbranch_vccnz .LBB0_1287
	s_andn2_b64 vcc, exec, s[18:19]
	s_cbranch_vccnz .LBB0_1286
	s_barrier
	s_branch .LBB0_1286
